# speedup vs baseline: 1.0088x; 1.0035x over previous
; __device__ __forceinline__ int opaque_tid() { int t = threadIdx.x; asm volatile("" : "+v"(t)); return t; }
; template <int AMODE>
; __device__ __forceinline__ void gemm_kloop(f32x4 (&acc)[4][4], const u16* __restrict__ A, int lda,
;                                            const u16* __restrict__ Bt, int ldb, int K, char* smem,
;                                            const float* __restrict__ ssq_rows) {
;     const int tid = opaque_tid(), lane = tid & 63, wid = tid >> 6, wr = wid >> 1, wc = wid & 1;
;     const int r = lane & 15, g4 = lane >> 4;
;     char* As = smem; char* Bs = smem + 32768;
;     const int grow = wid * 8 + (lane >> 3);
;     const int gch = ((lane & 7) ^ ((lane >> 3) & 7)) * 8;
;     const u16* Ag = A + (size_t)grow * lda + gch;
;     const u16* Bg = Bt + (size_t)grow * ldb + gch;
;     const int lrow = tid >> 3, lkc = tid & 7;
;     const u16* Ap = A + (size_t)lrow * lda + lkc * 8;
;     const int lds_w = lrow * 128 + ((lkc ^ (lrow & 7)) << 4);
;     uint4 ra[4];
;     float rs[4];
;     const int nk = K >> 6;
;     ...
;     GLOAD(0, 0);
;     LSTORE(0);
;     asm volatile("s_waitcnt vmcnt(0)" ::: "memory");
;     __syncthreads();
; __device__ void phaseA_tile(const Params& p, int l, int mt, int nt, char* smem) {
;     ...
;     const int m0 = mt * 128, n0 = nt * 128;
;     gemm_kloop<0>(acc, p.xb + (size_t)m0 * 1024, 1024, p.wt_in + ((size_t)l * NIN + n0) * 1024, 1024, 1024, smem, nullptr);
.LBB0_151:
	s_lshl_b32 s54, s52, 7
	s_ashr_i32 s55, s54, 31
	v_readlane_b32 s4, v214, 34
	s_lshl_b32 s56, s53, 7
	s_lshl_b64 s[0:1], s[54:55], 11
	v_readlane_b32 s10, v214, 40
	v_readlane_b32 s5, v214, 35
	v_readlane_b32 s11, v214, 41
	v_readlane_b32 s16, v214, 46
	v_readlane_b32 s17, v214, 47
	v_readlane_b32 s18, v214, 48
	v_readlane_b32 s19, v214, 49
	s_add_u32 s4, s10, s0
	v_readlane_b32 s6, v214, 36
	s_addc_u32 s5, s11, s1
	s_mov_b64 s[98:99], s[4:5]
	s_ashr_i32 s57, s56, 31
	s_mul_i32 s2, s48, 0x3080
	v_readlane_b32 s16, v214, 0
	v_mov_b32_e32 v70, v141
	v_readlane_b32 s7, v214, 37
	s_add_u32 s6, s2, s56
	v_readlane_b32 s17, v214, 1
	v_readlane_b32 s18, v214, 2
	v_readlane_b32 s19, v214, 3
	v_readlane_b32 s20, v214, 4
	v_readlane_b32 s21, v214, 5
	v_readlane_b32 s22, v214, 6
	v_readlane_b32 s23, v214, 7
	v_readlane_b32 s24, v214, 8
	v_readlane_b32 s25, v214, 9
	v_mov_b32_e32 v10, v141
	s_addc_u32 s7, 0, s57
	v_readlane_b32 s26, v214, 10
	v_readlane_b32 s27, v214, 11
	v_readlane_b32 s28, v214, 12
	v_readlane_b32 s29, v214, 13
	v_readlane_b32 s30, v214, 14
	v_readlane_b32 s31, v214, 15
	s_mov_b64 s[16:17], s[24:25]
	s_lshl_b64 s[6:7], s[6:7], 11
	v_ashrrev_i32_e32 v8, 6, v10
	v_bfe_u32 v0, v10, 3, 3
	s_mov_b64 s[22:23], s[30:31]
	v_lshl_or_b32 v2, v8, 3, v0
	s_add_u32 s6, s22, s6
	v_ashrrev_i32_e32 v3, 31, v2
	v_lshlrev_b32_e32 v71, 10, v8
	s_addc_u32 s7, s23, s7
	s_mov_b64 s[100:101], s[6:7]
	v_bitop3_b32 v0, v0, v10, 7 bitop3:0x78
	v_lshlrev_b64 v[2:3], 11, v[2:3]
	v_add_u32_e32 v8, 0x8000, v71
	v_lshlrev_b32_e32 v0, 4, v0
	v_lshl_add_u64 v[6:7], s[6:7], 0, v[2:3]
	v_readfirstlane_b32 s2, v8
	v_lshl_add_u64 v[4:5], s[4:5], 0, v[2:3]
	v_lshl_add_u64 v[6:7], v[6:7], 0, v[0:1]
	s_mov_b32 m0, s2
	v_readfirstlane_b32 s2, v71
	v_add_u32_e32 v12, 0x9000, v71
	v_lshl_add_u64 v[4:5], v[4:5], 0, v[0:1]
	global_load_lds_dwordx4 v[6:7], off
	s_mov_b32 m0, s2
	s_mov_b64 s[4:5], 0x10000
	v_readfirstlane_b32 s2, v12
	v_add_u32_e32 v12, 0x1000, v71
	global_load_lds_dwordx4 v[4:5], off
	v_lshl_add_u64 v[8:9], v[6:7], 0, s[4:5]
	s_mov_b32 m0, s2
	v_readfirstlane_b32 s2, v12
	v_add_u32_e32 v12, 0xa000, v71
	global_load_lds_dwordx4 v[8:9], off
	v_lshl_add_u64 v[8:9], v[4:5], 0, s[4:5]
	s_mov_b32 m0, s2
	s_mov_b64 s[4:5], 0x20000
	v_readfirstlane_b32 s2, v12
	v_add_u32_e32 v12, 0x2000, v71
	global_load_lds_dwordx4 v[8:9], off
	v_lshl_add_u64 v[8:9], v[6:7], 0, s[4:5]
	s_mov_b32 m0, s2
	v_readfirstlane_b32 s2, v12
	global_load_lds_dwordx4 v[8:9], off
	v_lshl_add_u64 v[8:9], v[4:5], 0, s[4:5]
	s_mov_b32 m0, s2
	s_mov_b64 s[4:5], 0x30000
	global_load_lds_dwordx4 v[8:9], off
	v_add_u32_e32 v8, 0xb000, v71
	v_lshl_add_u64 v[6:7], v[6:7], 0, s[4:5]
	v_readfirstlane_b32 s2, v8
	s_mov_b32 m0, s2
	v_lshl_add_u64 v[4:5], v[4:5], 0, s[4:5]
	global_load_lds_dwordx4 v[6:7], off
	v_add_u32_e32 v6, 0x3000, v71
	v_and_b32_e32 v11, 7, v10
	v_readfirstlane_b32 s2, v6
	s_mov_b32 m0, s2
	v_lshrrev_b32_e32 v6, 1, v10
	global_load_lds_dwordx4 v[4:5], off
	v_and_b32_e32 v5, 15, v10
	s_mov_b32 s2, 0x1ffffc0
	v_and_or_b32 v5, v6, s2, v5
	v_bfe_u32 v4, v10, 4, 2
	v_lshlrev_b32_e32 v73, 7, v5
	v_lshlrev_b32_e32 v5, 7, v10
	v_and_b32_e32 v72, 0x2780, v5
	v_bitop3_b32 v5, v4, v10, 7 bitop3:0x78
	v_bitop3_b32 v4, v4, v11, 4 bitop3:0x36
	s_lshl_b64 s[4:5], s[56:57], 11
	v_lshlrev_b32_e32 v76, 4, v5
	v_lshlrev_b32_e32 v74, 4, v4
	v_lshl_add_u64 v[4:5], s[4:5], 0, v[2:3]
	v_lshl_add_u64 v[2:3], s[0:1], 0, v[2:3]
	s_nop 0
	v_or_b32_e32 v2, v2, v0
	v_or_b32_e32 v4, v4, v0
	v_lshl_add_u64 v[68:69], s[10:11], 0, v[2:3]
	v_mov_b32_e32 v2, 0
	v_mov_b32_e32 v75, v70
	v_lshl_add_u64 v[66:67], s[44:45], 0, v[4:5]
	s_mov_b64 s[0:1], 0
	s_mov_b32 s2, 0
	v_mov_b32_e32 v3, v2
	v_mov_b32_e32 v4, v2
	v_mov_b32_e32 v5, v2
	v_mov_b32_e32 v6, v2
	v_mov_b32_e32 v7, v2
	v_mov_b32_e32 v8, v2
	v_mov_b32_e32 v9, v2
	v_mov_b32_e32 v10, v2
	v_mov_b32_e32 v11, v2
	v_mov_b32_e32 v12, v2
	v_mov_b32_e32 v13, v2
	v_mov_b32_e32 v14, v2
	v_mov_b32_e32 v15, v2
	v_mov_b32_e32 v16, v2
	v_mov_b32_e32 v17, v2
	v_mov_b32_e32 v18, v2
	v_mov_b32_e32 v19, v2
	v_mov_b32_e32 v20, v2
	v_mov_b32_e32 v21, v2
	v_mov_b32_e32 v22, v2
	v_mov_b32_e32 v23, v2
	v_mov_b32_e32 v24, v2
	v_mov_b32_e32 v25, v2
	v_mov_b32_e32 v26, v2
	v_mov_b32_e32 v27, v2
	v_mov_b32_e32 v28, v2
	v_mov_b32_e32 v29, v2
	v_mov_b32_e32 v30, v2
	v_mov_b32_e32 v31, v2
	v_mov_b32_e32 v32, v2
	v_mov_b32_e32 v33, v2
	v_mov_b32_e32 v34, v2
	v_mov_b32_e32 v35, v2
	v_mov_b32_e32 v36, v2
	v_mov_b32_e32 v37, v2
	v_mov_b32_e32 v38, v2
	v_mov_b32_e32 v39, v2
	v_mov_b32_e32 v40, v2
	v_mov_b32_e32 v41, v2
	v_mov_b32_e32 v42, v2
	v_mov_b32_e32 v43, v2
	v_mov_b32_e32 v44, v2
	v_mov_b32_e32 v45, v2
	v_mov_b32_e32 v46, v2
	v_mov_b32_e32 v47, v2
	v_mov_b32_e32 v48, v2
	v_mov_b32_e32 v49, v2
	v_mov_b32_e32 v50, v2
	v_mov_b32_e32 v51, v2
	v_mov_b32_e32 v52, v2
	v_mov_b32_e32 v53, v2
	v_mov_b32_e32 v54, v2
	v_mov_b32_e32 v55, v2
	v_mov_b32_e32 v56, v2
	v_mov_b32_e32 v57, v2
	v_mov_b32_e32 v58, v2
	v_mov_b32_e32 v59, v2
	v_mov_b32_e32 v60, v2
	v_mov_b32_e32 v61, v2
	v_mov_b32_e32 v62, v2
	v_mov_b32_e32 v63, v2
	v_mov_b32_e32 v64, v2
	v_mov_b32_e32 v65, v2
	v_readlane_b32 s8, v214, 38
	v_readlane_b32 s9, v214, 39
	v_readlane_b32 s12, v214, 42
	v_readlane_b32 s13, v214, 43
	v_readlane_b32 s14, v214, 44
	v_readlane_b32 s15, v214, 45
	s_mov_b64 s[18:19], s[26:27]
	s_mov_b64 s[20:21], s[28:29]
	s_waitcnt vmcnt(0) lgkmcnt(0)
	s_barrier
	v_lshrrev_b32_e32 v220, 6, v70
	v_bfe_u32 v221, v70, 3, 3
	v_lshl_or_b32 v216, v220, 3, v221
	v_and_b32_e32 v220, 7, v70
	v_xor_b32_e32 v220, v220, v221
	v_lshlrev_b32_e32 v220, 4, v220
	v_lshl_or_b32 v216, v216, 11, v220
	v_add_u32_e32 v217, 0x10000, v216
	v_add_u32_e32 v218, 0x20000, v216
	v_add_u32_e32 v219, 0x30000, v216
	v_readfirstlane_b32 s5, v71
	s_mov_b32 s0, 0
	s_mov_b32 s2, 0
	v_add_u32_e32 v0, s2, v73
	v_or_b32_e32 v77, s2, v72
	v_add_u32_e32 v90, v0, v76
	v_add_u32_e32 v102, v77, v76
	v_add_u32_e32 v0, v0, v74
	s_xor_b32 s4, s2, 0x4000
	s_add_u32 s4, s4, s5
	s_add_u32 s100, s100, 0x80
	s_addc_u32 s101, s101, 0
	s_add_u32 s98, s98, 0x80
	s_addc_u32 s99, s99, 0

; __device__ __forceinline__ int opaque_tid() { int t = threadIdx.x; asm volatile("" : "+v"(t)); return t; }
; template <int AMODE>
; __device__ __forceinline__ void gemm_kloop(f32x4 (&acc)[4][4], const u16* __restrict__ A, int lda,
;                                            const u16* __restrict__ Bt, int ldb, int K, char* smem,
;                                            const float* __restrict__ ssq_rows) {
;     const int tid = opaque_tid(), lane = tid & 63, wid = tid >> 6, wr = wid >> 1, wc = wid & 1;
;     const int r = lane & 15, g4 = lane >> 4;
;     char* As = smem; char* Bs = smem + 32768;
;     const int grow = wid * 8 + (lane >> 3);
;     const int gch = ((lane & 7) ^ ((lane >> 3) & 7)) * 8;
;     const u16* Ag = A + (size_t)grow * lda + gch;
;     const u16* Bg = Bt + (size_t)grow * ldb + gch;
;     const int lrow = tid >> 3, lkc = tid & 7;
;     const u16* Ap = A + (size_t)lrow * lda + lkc * 8;
;     const int lds_w = lrow * 128 + ((lkc ^ (lrow & 7)) << 4);
;     uint4 ra[4];
;     float rs[4];
;     const int nk = K >> 6;
;     ...
;     GLOAD(0, 0);
;     LSTORE(0);
;     asm volatile("s_waitcnt vmcnt(0)" ::: "memory");
;     __syncthreads();
; __device__ void phaseC1(const Params& p, int l, char* smem) {
;     ...
;         const int m0 = mt * 128, n0 = nt * 128;
;         f32x4 acc[4][4];
; #pragma unroll
;         for (int i = 0; i < 4; ++i)
; #pragma unroll
;             for (int j = 0; j < 4; ++j) acc[i][j] = (f32x4){0.f, 0.f, 0.f, 0.f};
;         gemm_kloop<0>(acc, p.ygb + (size_t)m0 * 2048, 2048, p.wt_m + ((size_t)l * 1024 + n0) * 2048, 2048, 2048, smem, nullptr);
.LBB0_706:
	s_lshl_b32 s8, s15, 7
	s_ashr_i32 s9, s8, 31
	v_readlane_b32 s36, v214, 34
	s_lshl_b32 s6, s16, 7
	s_lshl_b64 s[12:13], s[8:9], 12
	v_readlane_b32 s46, v214, 44
	v_readlane_b32 s47, v214, 45
	s_add_u32 s18, s46, s12
	s_addc_u32 s19, s47, s13
	s_ashr_i32 s7, s6, 31
	s_add_u32 s10, s6, s2
	v_mov_b32_e32 v10, v141
	s_addc_u32 s11, s7, 0
	s_lshl_b64 s[20:21], s[10:11], 12
	v_ashrrev_i32_e32 v8, 6, v10
	v_bfe_u32 v0, v10, 3, 3
	v_lshl_or_b32 v2, v8, 3, v0
	v_readlane_b32 s37, v214, 35
	s_add_u32 s20, s36, s20
	v_ashrrev_i32_e32 v3, 31, v2
	v_lshlrev_b32_e32 v70, 10, v8
	s_addc_u32 s21, s37, s21
	v_bitop3_b32 v0, v0, v10, 7 bitop3:0x78
	v_lshlrev_b64 v[2:3], 12, v[2:3]
	v_add_u32_e32 v8, 0x8000, v70
	v_lshlrev_b32_e32 v0, 4, v0
	v_lshl_add_u64 v[6:7], s[20:21], 0, v[2:3]
	v_readfirstlane_b32 s17, v8
	v_lshl_add_u64 v[4:5], s[18:19], 0, v[2:3]
	v_lshl_add_u64 v[6:7], v[6:7], 0, v[0:1]
	s_mov_b32 m0, s17
	v_readfirstlane_b32 s17, v70
	v_add_u32_e32 v12, 0x9000, v70
	v_lshl_add_u64 v[4:5], v[4:5], 0, v[0:1]
	global_load_lds_dwordx4 v[6:7], off
	s_mov_b32 m0, s17
	s_mov_b64 s[18:19], 0x20000
	v_readfirstlane_b32 s17, v12
	v_add_u32_e32 v12, 0x1000, v70
	global_load_lds_dwordx4 v[4:5], off
	v_lshl_add_u64 v[8:9], v[6:7], 0, s[18:19]
	s_mov_b32 m0, s17
	v_readfirstlane_b32 s17, v12
	v_add_u32_e32 v12, 0xa000, v70
	global_load_lds_dwordx4 v[8:9], off
	v_lshl_add_u64 v[8:9], v[4:5], 0, s[18:19]
	s_mov_b32 m0, s17
	s_mov_b64 s[18:19], 0x40000
	v_readfirstlane_b32 s17, v12
	v_add_u32_e32 v12, 0x2000, v70
	global_load_lds_dwordx4 v[8:9], off
	v_lshl_add_u64 v[8:9], v[6:7], 0, s[18:19]
	s_mov_b32 m0, s17
	v_readfirstlane_b32 s17, v12
	global_load_lds_dwordx4 v[8:9], off
	v_lshl_add_u64 v[8:9], v[4:5], 0, s[18:19]
	s_mov_b32 m0, s17
	s_mov_b64 s[18:19], 0x60000
	global_load_lds_dwordx4 v[8:9], off
	v_add_u32_e32 v8, 0xb000, v70
	v_lshl_add_u64 v[6:7], v[6:7], 0, s[18:19]
	v_readfirstlane_b32 s17, v8
	s_mov_b32 m0, s17
	v_lshl_add_u64 v[4:5], v[4:5], 0, s[18:19]
	global_load_lds_dwordx4 v[6:7], off
	v_add_u32_e32 v6, 0x3000, v70
	v_and_b32_e32 v11, 7, v10
	v_readfirstlane_b32 s17, v6
	s_mov_b32 m0, s17
	v_lshrrev_b32_e32 v6, 1, v10
	global_load_lds_dwordx4 v[4:5], off
	v_and_b32_e32 v5, 15, v10
	s_mov_b32 s17, 0x1ffffc0
	v_and_or_b32 v5, v6, s17, v5
	v_bfe_u32 v4, v10, 4, 2
	v_lshlrev_b32_e32 v72, 7, v5
	v_lshlrev_b32_e32 v5, 7, v10
	v_and_b32_e32 v71, 0x2780, v5
	v_bitop3_b32 v5, v4, v10, 7 bitop3:0x78
	v_bitop3_b32 v4, v4, v11, 4 bitop3:0x36
	s_lshl_b64 s[18:19], s[6:7], 12
	v_lshlrev_b32_e32 v74, 4, v5
	v_lshlrev_b32_e32 v73, 4, v4
	v_lshl_add_u64 v[4:5], s[18:19], 0, v[2:3]
	v_lshl_add_u64 v[2:3], s[12:13], 0, v[2:3]
	s_nop 0
	v_or_b32_e32 v2, v2, v0
	v_or_b32_e32 v4, v4, v0
	v_lshl_add_u64 v[68:69], s[46:47], 0, v[2:3]
	v_mov_b32_e32 v2, 0
	v_lshl_add_u64 v[66:67], s[0:1], 0, v[4:5]
	s_mov_b64 s[12:13], 0
	s_mov_b32 s17, 0
	v_mov_b32_e32 v3, v2
	v_mov_b32_e32 v4, v2
	v_mov_b32_e32 v5, v2
	v_mov_b32_e32 v6, v2
	v_mov_b32_e32 v7, v2
	v_mov_b32_e32 v8, v2
	v_mov_b32_e32 v9, v2
	v_mov_b32_e32 v10, v2
	v_mov_b32_e32 v11, v2
	v_mov_b32_e32 v12, v2
	v_mov_b32_e32 v13, v2
	v_mov_b32_e32 v14, v2
	v_mov_b32_e32 v15, v2
	v_mov_b32_e32 v16, v2
	v_mov_b32_e32 v17, v2
	v_mov_b32_e32 v18, v2
	v_mov_b32_e32 v19, v2
	v_mov_b32_e32 v20, v2
	v_mov_b32_e32 v21, v2
	v_mov_b32_e32 v22, v2
	v_mov_b32_e32 v23, v2
	v_mov_b32_e32 v24, v2
	v_mov_b32_e32 v25, v2
	v_mov_b32_e32 v26, v2
	v_mov_b32_e32 v27, v2
	v_mov_b32_e32 v28, v2
	v_mov_b32_e32 v29, v2
	v_mov_b32_e32 v30, v2
	v_mov_b32_e32 v31, v2
	v_mov_b32_e32 v32, v2
	v_mov_b32_e32 v33, v2
	v_mov_b32_e32 v34, v2
	v_mov_b32_e32 v35, v2
	v_mov_b32_e32 v36, v2
	v_mov_b32_e32 v37, v2
	v_mov_b32_e32 v38, v2
	v_mov_b32_e32 v39, v2
	v_mov_b32_e32 v40, v2
	v_mov_b32_e32 v41, v2
	v_mov_b32_e32 v42, v2
	v_mov_b32_e32 v43, v2
	v_mov_b32_e32 v44, v2
	v_mov_b32_e32 v45, v2
	v_mov_b32_e32 v46, v2
	v_mov_b32_e32 v47, v2
	v_mov_b32_e32 v48, v2
	v_mov_b32_e32 v49, v2
	v_mov_b32_e32 v50, v2
	v_mov_b32_e32 v51, v2
	v_mov_b32_e32 v52, v2
	v_mov_b32_e32 v53, v2
	v_mov_b32_e32 v54, v2
	v_mov_b32_e32 v55, v2
	v_mov_b32_e32 v56, v2
	v_mov_b32_e32 v57, v2
	v_mov_b32_e32 v58, v2
	v_mov_b32_e32 v59, v2
	v_mov_b32_e32 v60, v2
	v_mov_b32_e32 v61, v2
	v_mov_b32_e32 v62, v2
	v_mov_b32_e32 v63, v2
	v_mov_b32_e32 v64, v2
	v_mov_b32_e32 v65, v2
	s_mov_b64 s[20:21], 0x40080
	s_mov_b64 s[22:23], 0x60080
	v_readlane_b32 s38, v214, 36
	v_readlane_b32 s39, v214, 37
	v_readlane_b32 s40, v214, 38
	v_readlane_b32 s41, v214, 39
	v_readlane_b32 s42, v214, 40
	v_readlane_b32 s43, v214, 41
	v_readlane_b32 s44, v214, 42
	v_readlane_b32 s45, v214, 43
	v_readlane_b32 s48, v214, 46
	v_readlane_b32 s49, v214, 47
	v_readlane_b32 s50, v214, 48
	v_readlane_b32 s51, v214, 49
	s_waitcnt vmcnt(0) lgkmcnt(0)
	s_barrier
	v_lshrrev_b32_e32 v220, 6, v141
	v_bfe_u32 v221, v141, 3, 3
	v_lshl_or_b32 v216, v220, 3, v221
	v_and_b32_e32 v222, 7, v141
	v_xor_b32_e32 v222, v222, v221
	v_lshlrev_b32_e32 v222, 4, v222
	v_lshl_or_b32 v216, v216, 12, v222
	v_add_u32_e32 v217, 0x20000, v216
	v_add_u32_e32 v218, 0x40000, v216
	v_add_u32_e32 v219, 0x60000, v216
	v_readfirstlane_b32 s19, v220
	s_lshl_b32 s19, s19, 15
	v_readfirstlane_b32 s100, v66
	v_readfirstlane_b32 s101, v67
	s_sub_u32 s100, s100, s19
	s_subb_u32 s101, s101, 0
	v_readfirstlane_b32 s98, v68
	v_readfirstlane_b32 s99, v69
	s_sub_u32 s98, s98, s19
	s_subb_u32 s99, s99, 0
; #define MFMA(a, b, c) __builtin_amdgcn_mfma_f32_16x16x32_bf16((a), (b), (c), 0, 0, 0)
; template <int AMODE>
; __device__ __forceinline__ void gemm_kloop(f32x4 (&acc)[4][4], const u16* __restrict__ A, int lda,
;                                            const u16* __restrict__ Bt, int ldb, int K, char* smem,
;                                            const float* __restrict__ ssq_rows) {
;     ...
;     for (int kt = 0; kt < nk; ++kt) {
;         const int buf = kt & 1;
;         if (kt + 1 < nk) GLOAD(kt + 1, buf ^ 1);
;         const char* ab = As + buf * 16384 + (wr * 64 + r) * 128;
;         const char* bb = Bs + buf * 16384 + (wc * 64 + r) * 128;
;         bf16x8 af[2][4], bfr[2][4];
; #pragma unroll
;         for (int ks = 0; ks < 2; ++ks) {
;             const int co = ((ks * 4 + g4) ^ (r & 7)) << 4;
; #pragma unroll
;             for (int i = 0; i < 4; ++i) af[ks][i] = ld_frag(ab + i * 2048 + co);
; #pragma unroll
;             for (int j = 0; j < 4; ++j) bfr[ks][j] = ld_frag(bb + j * 2048 + co);
;         }
;         __builtin_amdgcn_sched_barrier(0);
;         __builtin_amdgcn_s_setprio(1);
; #pragma unroll
;         for (int ks = 0; ks < 2; ++ks)
; #pragma unroll
;             for (int i = 0; i < 4; ++i)
; #pragma unroll
;                 for (int j = 0; j < 4; ++j) acc[i][j] = MFMA(bfr[ks][j], af[ks][i], acc[i][j]);
;         __builtin_amdgcn_s_setprio(0);
;         __builtin_amdgcn_sched_barrier(0);
;         if (kt + 1 < nk) LSTORE(buf ^ 1);
;         asm volatile("s_waitcnt vmcnt(0)" ::: "memory");
;         __syncthreads();
;     }
.LBB0_707:
	s_setprio 1
	s_and_b32 s18, s17, 0x4000
	s_xor_b32 s19, s18, 0x4000
	v_add_u32_e32 v0, s19, v70
	s_add_u32 s100, s100, 0x80
	s_addc_u32 s101, s101, 0
	s_add_u32 s98, s98, 0x80
	s_addc_u32 s99, s99, 0
	v_readfirstlane_b32 s19, v0
	s_add_u32 m0, s19, 0x8000
	v_add_u32_e32 v0, s18, v72
	global_load_lds_dwordx4 v216, s[100:101]
	v_or_b32_e32 v75, s18, v71
	s_add_u32 m0, s19, 0x0
	v_add_u32_e32 v90, v0, v74
	global_load_lds_dwordx4 v216, s[98:99]
	v_add_u32_e32 v102, v75, v74
	s_add_u32 m0, s19, 0x9000
	v_add_u32_e32 v0, v0, v73
	global_load_lds_dwordx4 v217, s[100:101]
	ds_read_b128 v[76:79], v90
	s_add_u32 m0, s19, 0x1000
	ds_read_b128 v[80:83], v90 offset:2048
	global_load_lds_dwordx4 v217, s[98:99]
	ds_read_b128 v[84:87], v90 offset:4096
	s_add_u32 m0, s19, 0xa000
	ds_read_b128 v[90:93], v90 offset:6144
	global_load_lds_dwordx4 v218, s[100:101]
	ds_read_b128 v[94:97], v102 offset:32768
	s_add_u32 m0, s19, 0x2000
	ds_read_b128 v[98:101], v102 offset:34816
	global_load_lds_dwordx4 v218, s[98:99]
	ds_read_b128 v[110:113], v102 offset:36864
	s_add_u32 m0, s19, 0xb000
	ds_read_b128 v[114:117], v102 offset:38912
	global_load_lds_dwordx4 v219, s[100:101]
	ds_read_b128 v[118:121], v0
	s_add_u32 m0, s19, 0x3000
	ds_read_b128 v[122:125], v0 offset:2048
	global_load_lds_dwordx4 v219, s[98:99]
	ds_read_b128 v[126:129], v0 offset:4096
	ds_read_b128 v[130:133], v0 offset:6144
	v_add_u32_e32 v0, v75, v73
	ds_read_b128 v[134:137], v0 offset:32768
	ds_read_b128 v[142:145], v0 offset:34816
	ds_read_b128 v[146:149], v0 offset:36864
	ds_read_b128 v[150:153], v0 offset:38912
	s_setprio 0
	s_waitcnt lgkmcnt(0)
	v_mfma_f32_16x16x32_bf16 v[62:65], v[94:97], v[76:79], v[62:65]
	v_mfma_f32_16x16x32_bf16 v[58:61], v[98:101], v[76:79], v[58:61]
	v_mfma_f32_16x16x32_bf16 v[54:57], v[110:113], v[76:79], v[54:57]
	v_mfma_f32_16x16x32_bf16 v[50:53], v[114:117], v[76:79], v[50:53]
	v_mfma_f32_16x16x32_bf16 v[46:49], v[94:97], v[80:83], v[46:49]
	v_mfma_f32_16x16x32_bf16 v[42:45], v[98:101], v[80:83], v[42:45]
	v_mfma_f32_16x16x32_bf16 v[38:41], v[110:113], v[80:83], v[38:41]
	v_mfma_f32_16x16x32_bf16 v[34:37], v[114:117], v[80:83], v[34:37]
	v_mfma_f32_16x16x32_bf16 v[30:33], v[94:97], v[84:87], v[30:33]
	v_mfma_f32_16x16x32_bf16 v[26:29], v[98:101], v[84:87], v[26:29]
	v_mfma_f32_16x16x32_bf16 v[22:25], v[110:113], v[84:87], v[22:25]
	v_mfma_f32_16x16x32_bf16 v[18:21], v[114:117], v[84:87], v[18:21]
	v_mfma_f32_16x16x32_bf16 v[14:17], v[94:97], v[90:93], v[14:17]
	v_mfma_f32_16x16x32_bf16 v[10:13], v[98:101], v[90:93], v[10:13]
	v_mfma_f32_16x16x32_bf16 v[6:9], v[110:113], v[90:93], v[6:9]
	v_mfma_f32_16x16x32_bf16 v[2:5], v[114:117], v[90:93], v[2:5]
	v_mfma_f32_16x16x32_bf16 v[62:65], v[134:137], v[118:121], v[62:65]
	v_mfma_f32_16x16x32_bf16 v[58:61], v[142:145], v[118:121], v[58:61]
	v_mfma_f32_16x16x32_bf16 v[54:57], v[146:149], v[118:121], v[54:57]
	v_mfma_f32_16x16x32_bf16 v[50:53], v[150:153], v[118:121], v[50:53]
	v_mfma_f32_16x16x32_bf16 v[46:49], v[134:137], v[122:125], v[46:49]
	v_mfma_f32_16x16x32_bf16 v[42:45], v[142:145], v[122:125], v[42:45]
	v_mfma_f32_16x16x32_bf16 v[38:41], v[146:149], v[122:125], v[38:41]
	v_mfma_f32_16x16x32_bf16 v[34:37], v[150:153], v[122:125], v[34:37]
	v_mfma_f32_16x16x32_bf16 v[30:33], v[134:137], v[126:129], v[30:33]
	v_mfma_f32_16x16x32_bf16 v[26:29], v[142:145], v[126:129], v[26:29]
	v_mfma_f32_16x16x32_bf16 v[22:25], v[146:149], v[126:129], v[22:25]
	v_mfma_f32_16x16x32_bf16 v[18:21], v[150:153], v[126:129], v[18:21]
	v_mfma_f32_16x16x32_bf16 v[14:17], v[134:137], v[130:133], v[14:17]
	v_mfma_f32_16x16x32_bf16 v[10:13], v[142:145], v[130:133], v[10:13]
	v_mfma_f32_16x16x32_bf16 v[6:9], v[146:149], v[130:133], v[6:9]
	v_mfma_f32_16x16x32_bf16 v[2:5], v[150:153], v[130:133], v[2:5]
	s_nop 0
	s_waitcnt vmcnt(0)
	s_add_u32 s12, s12, 0x80
	s_addc_u32 s13, s13, 0
	s_addk_i32 s17, 0x4000
	s_cmpk_eq_i32 s12, 0xf80
	s_waitcnt vmcnt(0)
	s_barrier
	s_cbranch_scc0 .LBB0_707
	v_add_u32_e32 v0, v72, v74
	ds_read_b128 v[66:69], v0 offset:16384
	ds_read_b128 v[76:79], v0 offset:18432
	ds_read_b128 v[80:83], v0 offset:20480
	ds_read_b128 v[84:87], v0 offset:22528
	v_add_u32_e32 v0, v71, v74
	ds_read_b128 v[90:93], v0 offset:49152
	ds_read_b128 v[94:97], v0 offset:51200
	ds_read_b128 v[98:101], v0 offset:53248
	ds_read_b128 v[110:113], v0 offset:55296
	v_add_u32_e32 v0, v72, v73
	ds_read_b128 v[114:117], v0 offset:16384
	ds_read_b128 v[118:121], v0 offset:18432
	ds_read_b128 v[122:125], v0 offset:20480
	ds_read_b128 v[126:129], v0 offset:22528
	v_add_u32_e32 v0, v71, v73
	ds_read_b128 v[70:73], v0 offset:49152
	ds_read_b128 v[130:133], v0 offset:51200
	ds_read_b128 v[134:137], v0 offset:53248
	ds_read_b128 v[142:145], v0 offset:55296
	s_setprio 1
	s_waitcnt lgkmcnt(11)
	v_mfma_f32_16x16x32_bf16 v[62:65], v[90:93], v[66:69], v[62:65]
	s_waitcnt lgkmcnt(10)
	v_mfma_f32_16x16x32_bf16 v[58:61], v[94:97], v[66:69], v[58:61]
	s_waitcnt lgkmcnt(9)
	v_mfma_f32_16x16x32_bf16 v[54:57], v[98:101], v[66:69], v[54:57]
	s_waitcnt lgkmcnt(8)
	v_mfma_f32_16x16x32_bf16 v[50:53], v[110:113], v[66:69], v[50:53]
	v_mfma_f32_16x16x32_bf16 v[46:49], v[90:93], v[76:79], v[46:49]
	v_mfma_f32_16x16x32_bf16 v[42:45], v[94:97], v[76:79], v[42:45]
	v_mfma_f32_16x16x32_bf16 v[38:41], v[98:101], v[76:79], v[38:41]
	v_mfma_f32_16x16x32_bf16 v[34:37], v[110:113], v[76:79], v[34:37]
	v_mfma_f32_16x16x32_bf16 v[66:69], v[90:93], v[80:83], v[30:33]
	v_mfma_f32_16x16x32_bf16 v[26:29], v[94:97], v[80:83], v[26:29]
	v_mfma_f32_16x16x32_bf16 v[74:77], v[98:101], v[80:83], v[22:25]
	v_mfma_f32_16x16x32_bf16 v[78:81], v[110:113], v[80:83], v[18:21]
	v_mfma_f32_16x16x32_bf16 v[90:93], v[90:93], v[84:87], v[14:17]
	v_mfma_f32_16x16x32_bf16 v[10:13], v[94:97], v[84:87], v[10:13]
	v_mfma_f32_16x16x32_bf16 v[6:9], v[98:101], v[84:87], v[6:9]
	v_mfma_f32_16x16x32_bf16 v[2:5], v[110:113], v[84:87], v[2:5]
	s_waitcnt lgkmcnt(3)
; __device__ __forceinline__ float bf_lo(unsigned u) { return __uint_as_float(u << 16); }
; __device__ __forceinline__ float bf_hi(unsigned u) { return __uint_as_float(u & 0xffff0000u); }
; __device__ __forceinline__ float frcp(float x) { return __builtin_amdgcn_rcpf(x); }
; #define MFMA(a, b, c) __builtin_amdgcn_mfma_f32_16x16x32_bf16((a), (b), (c), 0, 0, 0)
; template <int AMODE>
; __device__ __forceinline__ void gemm_kloop(f32x4 (&acc)[4][4], const u16* __restrict__ A, int lda,
;                                            const u16* __restrict__ Bt, int ldb, int K, char* smem,
;                                            const float* __restrict__ ssq_rows) {
;     ...
;         for (int ks = 0; ks < 2; ++ks)
; #pragma unroll
;             for (int i = 0; i < 4; ++i)
; #pragma unroll
;                 for (int j = 0; j < 4; ++j) acc[i][j] = MFMA(bfr[ks][j], af[ks][i], acc[i][j]);
; __device__ void phaseC1(const Params& p, int l, char* smem) {
;     ...
; #pragma unroll
;         for (int i = 0; i < 4; ++i) {
;             const size_t row = (size_t)(m0 + wr * 64 + i * 16 + r);
; #pragma unroll
;             for (int j = 0; j < 4; ++j) {
;                 const int col = n0 + wc * 64 + j * 16 + g4 * 4;
;                 const uint2 gm = *(const uint2*)(p.gmb + row * 1024 + col);
;                 const uint2 ga = *(const uint2*)(p.gab + row * 1024 + col);
;                 acc[i][j][0] *= bf_lo(gm.x) * frcp(bf_lo(ga.x)); acc[i][j][1] *= bf_hi(gm.x) * frcp(bf_hi(ga.x));
;                 acc[i][j][2] *= bf_lo(gm.y) * frcp(bf_lo(ga.y)); acc[i][j][3] *= bf_hi(gm.y) * frcp(bf_hi(ga.y));
;             }
;         }
	v_mfma_f32_16x16x32_bf16 v[82:85], v[70:73], v[114:117], v[62:65]
	s_waitcnt lgkmcnt(2)
	v_mfma_f32_16x16x32_bf16 v[94:97], v[130:133], v[114:117], v[58:61]
	s_waitcnt lgkmcnt(1)
	v_mfma_f32_16x16x32_bf16 v[98:101], v[134:137], v[114:117], v[54:57]
	s_waitcnt lgkmcnt(0)
	v_mfma_f32_16x16x32_bf16 v[14:17], v[142:145], v[114:117], v[50:53]
	v_mfma_f32_16x16x32_bf16 v[18:21], v[70:73], v[118:121], v[46:49]
	v_mfma_f32_16x16x32_bf16 v[22:25], v[130:133], v[118:121], v[42:45]
	v_mfma_f32_16x16x32_bf16 v[30:33], v[134:137], v[118:121], v[38:41]
	v_mfma_f32_16x16x32_bf16 v[38:41], v[142:145], v[118:121], v[34:37]
	v_mfma_f32_16x16x32_bf16 v[46:49], v[70:73], v[122:125], v[66:69]
	v_mfma_f32_16x16x32_bf16 v[54:57], v[130:133], v[122:125], v[26:29]
	v_mfma_f32_16x16x32_bf16 v[62:65], v[134:137], v[122:125], v[74:77]
	v_mfma_f32_16x16x32_bf16 v[58:61], v[142:145], v[122:125], v[78:81]
	v_mfma_f32_16x16x32_bf16 v[50:53], v[70:73], v[126:129], v[90:93]
	v_mfma_f32_16x16x32_bf16 v[42:45], v[130:133], v[126:129], v[10:13]
	v_mfma_f32_16x16x32_bf16 v[34:37], v[134:137], v[126:129], v[6:9]
	v_mfma_f32_16x16x32_bf16 v[26:29], v[142:145], v[126:129], v[2:5]
	s_setprio 0
	v_add_u32_e32 v80, s8, v88
	s_nop 0
	v_or_b32_e32 v2, s6, v89
	v_ashrrev_i32_e32 v81, 31, v80
	v_readlane_b32 s40, v214, 50
	v_ashrrev_i32_e32 v3, 31, v2
	v_lshlrev_b64 v[4:5], 11, v[80:81]
	v_readlane_b32 s50, v214, 60
	v_readlane_b32 s51, v214, 61
	v_readlane_b32 s52, v214, 62
	v_readlane_b32 s53, v214, 63
	v_lshl_add_u64 v[6:7], s[50:51], 0, v[4:5]
	v_lshlrev_b64 v[66:67], 1, v[2:3]
	v_lshl_add_u64 v[4:5], s[52:53], 0, v[4:5]
	v_lshl_add_u64 v[68:69], v[4:5], 0, v[66:67]
	s_waitcnt vmcnt(0)
	s_barrier
	global_load_dwordx2 v[4:5], v[68:69], off
	v_lshl_add_u64 v[72:73], v[6:7], 0, v[66:67]
	global_load_dwordx2 v[228:229], v[72:73], off
	global_load_dwordx2 v[230:231], v[72:73], off offset:32
	global_load_dwordx2 v[232:233], v[68:69], off offset:32
	global_load_dwordx2 v[234:235], v[72:73], off offset:64
	global_load_dwordx2 v[236:237], v[68:69], off offset:64
	global_load_dwordx2 v[238:239], v[72:73], off offset:96
	global_load_dwordx2 v[240:241], v[68:69], off offset:96
	v_lshlrev_b64 v[70:71], 10, v[80:81]
	v_readlane_b32 s41, v214, 51
	v_readlane_b32 s42, v214, 52
	v_readlane_b32 s43, v214, 53
	v_readlane_b32 s44, v214, 54
	v_readlane_b32 s45, v214, 55
	v_readlane_b32 s46, v214, 56
	v_readlane_b32 s47, v214, 57
	v_readlane_b32 s48, v214, 58
	v_readlane_b32 s49, v214, 59
	v_readlane_b32 s54, v213, 0
	s_lshl_b64 s[8:9], s[8:9], 11
	v_readlane_b32 s55, v213, 1
	s_add_u32 s12, s54, s8
	s_addc_u32 s13, s55, s9
	s_lshl_b64 s[10:11], s[10:11], 11
	s_waitcnt vmcnt(7)
	v_lshlrev_b32_e32 v0, 16, v4
	v_rcp_f32_e32 v8, v0
	v_and_b32_e32 v0, 0xffff0000, v4
	v_rcp_f32_e32 v9, v0
	v_lshlrev_b32_e32 v0, 16, v5
	v_rcp_f32_e32 v4, v0
	v_and_b32_e32 v0, 0xffff0000, v5
	v_rcp_f32_e32 v5, v0
	s_waitcnt vmcnt(6)
	v_lshlrev_b32_e32 v6, 16, v228
	v_and_b32_e32 v7, 0xffff0000, v228
	v_lshlrev_b32_e32 v2, 16, v229
	v_and_b32_e32 v3, 0xffff0000, v229
	v_pk_mul_f32 v[6:7], v[8:9], v[6:7]
	v_pk_mul_f32 v[2:3], v[4:5], v[2:3]
	s_nop 0
	v_pk_mul_f32 v[4:5], v[84:85], v[2:3]
	v_pk_mul_f32 v[2:3], v[82:83], v[6:7]
	s_waitcnt vmcnt(5)
	v_lshlrev_b32_e32 v10, 16, v230
	s_waitcnt vmcnt(4)
	v_lshlrev_b32_e32 v0, 16, v232
	v_rcp_f32_e32 v12, v0
	v_and_b32_e32 v0, 0xffff0000, v232
	v_rcp_f32_e32 v13, v0
	v_lshlrev_b32_e32 v0, 16, v233
	v_rcp_f32_e32 v8, v0
	v_and_b32_e32 v0, 0xffff0000, v233
	v_rcp_f32_e32 v9, v0
	v_and_b32_e32 v11, 0xffff0000, v230
	v_lshlrev_b32_e32 v6, 16, v231
	v_and_b32_e32 v7, 0xffff0000, v231
	v_pk_mul_f32 v[10:11], v[12:13], v[10:11]
	v_pk_mul_f32 v[6:7], v[8:9], v[6:7]
	s_nop 0
	v_pk_mul_f32 v[8:9], v[96:97], v[6:7]
	v_pk_mul_f32 v[6:7], v[94:95], v[10:11]
	v_mov_b32_e32 v96, v141
	s_waitcnt vmcnt(3)
	v_lshlrev_b32_e32 v74, 16, v234
	s_waitcnt vmcnt(2)
	v_lshlrev_b32_e32 v0, 16, v236
	v_rcp_f32_e32 v76, v0
	v_and_b32_e32 v0, 0xffff0000, v236
	v_rcp_f32_e32 v77, v0
	v_lshlrev_b32_e32 v0, 16, v237
	v_rcp_f32_e32 v12, v0
	v_and_b32_e32 v0, 0xffff0000, v237
	v_rcp_f32_e32 v13, v0
	v_and_b32_e32 v75, 0xffff0000, v234
	v_lshlrev_b32_e32 v10, 16, v235
	v_and_b32_e32 v11, 0xffff0000, v235
	v_pk_mul_f32 v[74:75], v[76:77], v[74:75]
	v_pk_mul_f32 v[10:11], v[12:13], v[10:11]
	s_nop 0
	v_pk_mul_f32 v[12:13], v[100:101], v[10:11]
	v_pk_mul_f32 v[10:11], v[98:99], v[74:75]
	s_nop 0
	s_waitcnt vmcnt(1)
	v_lshlrev_b32_e32 v76, 16, v238
	s_waitcnt vmcnt(0)
	v_lshlrev_b32_e32 v0, 16, v240
	v_rcp_f32_e32 v78, v0
	v_and_b32_e32 v0, 0xffff0000, v240
	v_rcp_f32_e32 v79, v0
	v_lshlrev_b32_e32 v0, 16, v241
	v_rcp_f32_e32 v74, v0
	v_and_b32_e32 v0, 0xffff0000, v241
	v_rcp_f32_e32 v75, v0
	v_and_b32_e32 v77, 0xffff0000, v238
	v_lshlrev_b32_e32 v72, 16, v239
	v_and_b32_e32 v73, 0xffff0000, v239
	v_pk_mul_f32 v[72:73], v[74:75], v[72:73]
	v_pk_mul_f32 v[76:77], v[78:79], v[76:77]
	v_pk_mul_f32 v[16:17], v[16:17], v[72:73]
	v_or_b32_e32 v72, 16, v80
	v_ashrrev_i32_e32 v73, 31, v72
	v_lshlrev_b64 v[74:75], 10, v[72:73]
	v_lshlrev_b64 v[72:73], 11, v[72:73]
	v_pk_mul_f32 v[14:15], v[14:15], v[76:77]
	v_lshl_add_u64 v[76:77], s[50:51], 0, v[72:73]
	v_lshl_add_u64 v[72:73], s[52:53], 0, v[72:73]
	v_lshl_add_u64 v[72:73], v[72:73], 0, v[66:67]
	global_load_dwordx2 v[82:83], v[72:73], off
	v_lshl_add_u64 v[76:77], v[76:77], 0, v[66:67]
	global_load_dwordx2 v[228:229], v[76:77], off
	global_load_dwordx2 v[230:231], v[76:77], off offset:32
	global_load_dwordx2 v[232:233], v[72:73], off offset:32
	global_load_dwordx2 v[234:235], v[76:77], off offset:64
	global_load_dwordx2 v[236:237], v[72:73], off offset:64
	global_load_dwordx2 v[238:239], v[76:77], off offset:96
	global_load_dwordx2 v[240:241], v[72:73], off offset:96
	s_waitcnt vmcnt(7)
; __device__ __forceinline__ float bf_lo(unsigned u) { return __uint_as_float(u << 16); }
; __device__ __forceinline__ float bf_hi(unsigned u) { return __uint_as_float(u & 0xffff0000u); }
; __device__ __forceinline__ float frcp(float x) { return __builtin_amdgcn_rcpf(x); }
; __device__ void phaseC1(const Params& p, int l, char* smem) {
;     ...
; #pragma unroll
;         for (int i = 0; i < 4; ++i) {
;             const size_t row = (size_t)(m0 + wr * 64 + i * 16 + r);
; #pragma unroll
;             for (int j = 0; j < 4; ++j) {
;                 const int col = n0 + wc * 64 + j * 16 + g4 * 4;
;                 const uint2 gm = *(const uint2*)(p.gmb + row * 1024 + col);
;                 const uint2 ga = *(const uint2*)(p.gab + row * 1024 + col);
;                 acc[i][j][0] *= bf_lo(gm.x) * frcp(bf_lo(ga.x)); acc[i][j][1] *= bf_hi(gm.x) * frcp(bf_hi(ga.x));
;                 acc[i][j][2] *= bf_lo(gm.y) * frcp(bf_lo(ga.y)); acc[i][j][3] *= bf_hi(gm.y) * frcp(bf_hi(ga.y));
;             }
;         }
	v_lshlrev_b32_e32 v0, 16, v82
	v_rcp_f32_e32 v86, v0
	v_and_b32_e32 v0, 0xffff0000, v82
	v_rcp_f32_e32 v87, v0
	v_lshlrev_b32_e32 v0, 16, v83
	v_rcp_f32_e32 v82, v0
	v_and_b32_e32 v0, 0xffff0000, v83
	v_rcp_f32_e32 v83, v0
	s_waitcnt vmcnt(6)
	v_lshlrev_b32_e32 v84, 16, v228
	v_and_b32_e32 v85, 0xffff0000, v228
	v_lshlrev_b32_e32 v78, 16, v229
	v_and_b32_e32 v79, 0xffff0000, v229
	v_pk_mul_f32 v[78:79], v[82:83], v[78:79]
	v_pk_mul_f32 v[84:85], v[86:87], v[84:85]
	v_pk_mul_f32 v[20:21], v[20:21], v[78:79]
	v_pk_mul_f32 v[18:19], v[18:19], v[84:85]
	s_waitcnt vmcnt(5)
	v_lshlrev_b32_e32 v84, 16, v230
	s_waitcnt vmcnt(4)
	v_lshlrev_b32_e32 v0, 16, v232
	v_rcp_f32_e32 v86, v0
	v_and_b32_e32 v0, 0xffff0000, v232
	v_rcp_f32_e32 v87, v0
	v_lshlrev_b32_e32 v0, 16, v233
	v_rcp_f32_e32 v82, v0
	v_and_b32_e32 v0, 0xffff0000, v233
	v_rcp_f32_e32 v83, v0
	v_and_b32_e32 v85, 0xffff0000, v230
	v_lshlrev_b32_e32 v78, 16, v231
	v_and_b32_e32 v79, 0xffff0000, v231
	v_pk_mul_f32 v[78:79], v[82:83], v[78:79]
	v_pk_mul_f32 v[84:85], v[86:87], v[84:85]
	v_pk_mul_f32 v[24:25], v[24:25], v[78:79]
	v_pk_mul_f32 v[22:23], v[22:23], v[84:85]
	s_waitcnt vmcnt(3)
	v_lshlrev_b32_e32 v84, 16, v234
	s_waitcnt vmcnt(2)
	v_lshlrev_b32_e32 v0, 16, v236
	v_rcp_f32_e32 v86, v0
	v_and_b32_e32 v0, 0xffff0000, v236
	v_rcp_f32_e32 v87, v0
	v_lshlrev_b32_e32 v0, 16, v237
	v_rcp_f32_e32 v82, v0
	v_and_b32_e32 v0, 0xffff0000, v237
	v_rcp_f32_e32 v83, v0
	v_and_b32_e32 v85, 0xffff0000, v234
	v_lshlrev_b32_e32 v78, 16, v235
	v_and_b32_e32 v79, 0xffff0000, v235
	v_pk_mul_f32 v[78:79], v[82:83], v[78:79]
	v_pk_mul_f32 v[84:85], v[86:87], v[84:85]
	v_pk_mul_f32 v[32:33], v[32:33], v[78:79]
	s_nop 0
	v_pk_mul_f32 v[30:31], v[30:31], v[84:85]
	s_waitcnt vmcnt(1)
	v_lshlrev_b32_e32 v82, 16, v238
	s_waitcnt vmcnt(0)
	v_lshlrev_b32_e32 v0, 16, v240
	v_rcp_f32_e32 v84, v0
	v_and_b32_e32 v0, 0xffff0000, v240
	v_rcp_f32_e32 v85, v0
	v_lshlrev_b32_e32 v0, 16, v241
	v_rcp_f32_e32 v78, v0
	v_and_b32_e32 v0, 0xffff0000, v241
	v_rcp_f32_e32 v79, v0
	v_and_b32_e32 v83, 0xffff0000, v238
	v_lshlrev_b32_e32 v76, 16, v239
	v_and_b32_e32 v77, 0xffff0000, v239
	v_pk_mul_f32 v[76:77], v[78:79], v[76:77]
	v_pk_mul_f32 v[82:83], v[84:85], v[82:83]
	v_pk_mul_f32 v[40:41], v[40:41], v[76:77]
	v_or_b32_e32 v76, 32, v80
	v_ashrrev_i32_e32 v77, 31, v76
	v_lshlrev_b64 v[78:79], 10, v[76:77]
	v_lshlrev_b64 v[76:77], 11, v[76:77]
	v_pk_mul_f32 v[38:39], v[38:39], v[82:83]
	v_lshl_add_u64 v[82:83], s[50:51], 0, v[76:77]
	v_lshl_add_u64 v[76:77], s[52:53], 0, v[76:77]
	v_lshl_add_u64 v[76:77], v[76:77], 0, v[66:67]
	global_load_dwordx2 v[86:87], v[76:77], off
	v_lshl_add_u64 v[82:83], v[82:83], 0, v[66:67]
	global_load_dwordx2 v[228:229], v[82:83], off
	global_load_dwordx2 v[230:231], v[82:83], off offset:32
	global_load_dwordx2 v[232:233], v[76:77], off offset:32
	global_load_dwordx2 v[234:235], v[82:83], off offset:64
	global_load_dwordx2 v[236:237], v[76:77], off offset:64
	global_load_dwordx2 v[238:239], v[82:83], off offset:96
	global_load_dwordx2 v[240:241], v[76:77], off offset:96
	v_or_b32_e32 v80, 48, v80
	v_ashrrev_i32_e32 v81, 31, v80
	s_waitcnt vmcnt(7)
	v_lshlrev_b32_e32 v0, 16, v86
	v_rcp_f32_e32 v92, v0
	v_and_b32_e32 v0, 0xffff0000, v86
	v_rcp_f32_e32 v93, v0
	v_lshlrev_b32_e32 v0, 16, v87
	v_rcp_f32_e32 v86, v0
	v_and_b32_e32 v0, 0xffff0000, v87
	v_rcp_f32_e32 v87, v0
	s_waitcnt vmcnt(6)
	v_lshlrev_b32_e32 v90, 16, v228
	v_and_b32_e32 v91, 0xffff0000, v228
	v_lshlrev_b32_e32 v84, 16, v229
	v_and_b32_e32 v85, 0xffff0000, v229
	v_pk_mul_f32 v[84:85], v[86:87], v[84:85]
	v_pk_mul_f32 v[90:91], v[92:93], v[90:91]
	v_pk_mul_f32 v[48:49], v[48:49], v[84:85]
	v_pk_mul_f32 v[46:47], v[46:47], v[90:91]
	s_waitcnt vmcnt(5)
	v_lshlrev_b32_e32 v90, 16, v230
	s_waitcnt vmcnt(4)
	v_lshlrev_b32_e32 v0, 16, v232
	v_rcp_f32_e32 v92, v0
	v_and_b32_e32 v0, 0xffff0000, v232
	v_rcp_f32_e32 v93, v0
	v_lshlrev_b32_e32 v0, 16, v233
	v_rcp_f32_e32 v86, v0
	v_and_b32_e32 v0, 0xffff0000, v233
	v_rcp_f32_e32 v87, v0
	v_and_b32_e32 v91, 0xffff0000, v230
	v_lshlrev_b32_e32 v84, 16, v231
	v_and_b32_e32 v85, 0xffff0000, v231
	v_pk_mul_f32 v[84:85], v[86:87], v[84:85]
	v_pk_mul_f32 v[90:91], v[92:93], v[90:91]
	v_pk_mul_f32 v[56:57], v[56:57], v[84:85]
	v_pk_mul_f32 v[54:55], v[54:55], v[90:91]
	s_waitcnt vmcnt(3)
	v_lshlrev_b32_e32 v90, 16, v234
	s_waitcnt vmcnt(2)
	v_lshlrev_b32_e32 v0, 16, v236
	v_rcp_f32_e32 v92, v0
	v_and_b32_e32 v0, 0xffff0000, v236
	v_rcp_f32_e32 v93, v0
	v_lshlrev_b32_e32 v0, 16, v237
	v_rcp_f32_e32 v86, v0
	v_and_b32_e32 v0, 0xffff0000, v237
	v_rcp_f32_e32 v87, v0
	v_and_b32_e32 v91, 0xffff0000, v234
	v_lshlrev_b32_e32 v84, 16, v235
	v_and_b32_e32 v85, 0xffff0000, v235
	v_pk_mul_f32 v[84:85], v[86:87], v[84:85]
	v_pk_mul_f32 v[90:91], v[92:93], v[90:91]
	v_pk_mul_f32 v[64:65], v[64:65], v[84:85]
	s_nop 0
	v_pk_mul_f32 v[62:63], v[62:63], v[90:91]
	s_waitcnt vmcnt(1)
	v_lshlrev_b32_e32 v86, 16, v238
	s_waitcnt vmcnt(0)
; __device__ __forceinline__ float bf_lo(unsigned u) { return __uint_as_float(u << 16); }
; __device__ __forceinline__ float bf_hi(unsigned u) { return __uint_as_float(u & 0xffff0000u); }
; __device__ __forceinline__ float frcp(float x) { return __builtin_amdgcn_rcpf(x); }
; __device__ __forceinline__ int opaque_tid() { int t = threadIdx.x; asm volatile("" : "+v"(t)); return t; }
; template <int AMODE>
; __device__ __forceinline__ void gemm_kloop(f32x4 (&acc)[4][4], const u16* __restrict__ A, int lda,
;                                            const u16* __restrict__ Bt, int ldb, int K, char* smem,
;                                            const float* __restrict__ ssq_rows) {
;     const int tid = opaque_tid(), lane = tid & 63, wid = tid >> 6, wr = wid >> 1, wc = wid & 1;
;     const int r = lane & 15, g4 = lane >> 4;
;     char* As = smem; char* Bs = smem + 32768;
;     const int grow = wid * 8 + (lane >> 3);
;     const int gch = ((lane & 7) ^ ((lane >> 3) & 7)) * 8;
;     const u16* Ag = A + (size_t)grow * lda + gch;
;     const u16* Bg = Bt + (size_t)grow * ldb + gch;
;     const int lrow = tid >> 3, lkc = tid & 7;
;     const u16* Ap = A + (size_t)lrow * lda + lkc * 8;
;     const int lds_w = lrow * 128 + ((lkc ^ (lrow & 7)) << 4);
;     uint4 ra[4];
;     float rs[4];
;     const int nk = K >> 6;
;     ...
;     GLOAD(0, 0);
;     LSTORE(0);
;     asm volatile("s_waitcnt vmcnt(0)" ::: "memory");
;     __syncthreads();
; __device__ void phaseC1(const Params& p, int l, char* smem) {
;     ...
; #pragma unroll
;         for (int i = 0; i < 4; ++i) {
;             const size_t row = (size_t)(m0 + wr * 64 + i * 16 + r);
; #pragma unroll
;             for (int j = 0; j < 4; ++j) {
;                 const int col = n0 + wc * 64 + j * 16 + g4 * 4;
;                 const uint2 gm = *(const uint2*)(p.gmb + row * 1024 + col);
;                 const uint2 ga = *(const uint2*)(p.gab + row * 1024 + col);
;                 acc[i][j][0] *= bf_lo(gm.x) * frcp(bf_lo(ga.x)); acc[i][j][1] *= bf_hi(gm.x) * frcp(bf_hi(ga.x));
;                 acc[i][j][2] *= bf_lo(gm.y) * frcp(bf_lo(ga.y)); acc[i][j][3] *= bf_hi(gm.y) * frcp(bf_hi(ga.y));
;             }
;         }
;         gemm_kloop<0>(acc, p.yab + (size_t)m0 * 1024, 1024, p.wt_a + ((size_t)l * 1024 + n0) * 1024, 1024, 1024, smem, nullptr);
	v_lshlrev_b32_e32 v0, 16, v240
	v_rcp_f32_e32 v90, v0
	v_and_b32_e32 v0, 0xffff0000, v240
	v_rcp_f32_e32 v91, v0
	v_lshlrev_b32_e32 v0, 16, v241
	v_rcp_f32_e32 v84, v0
	v_and_b32_e32 v0, 0xffff0000, v241
	v_rcp_f32_e32 v85, v0
	v_and_b32_e32 v87, 0xffff0000, v238
	v_lshlrev_b32_e32 v82, 16, v239
	v_and_b32_e32 v83, 0xffff0000, v239
	v_pk_mul_f32 v[82:83], v[84:85], v[82:83]
	v_pk_mul_f32 v[86:87], v[90:91], v[86:87]
	v_pk_mul_f32 v[60:61], v[60:61], v[82:83]
	v_lshlrev_b64 v[82:83], 10, v[80:81]
	v_lshlrev_b64 v[80:81], 11, v[80:81]
	v_lshl_add_u64 v[84:85], s[50:51], 0, v[80:81]
	v_lshl_add_u64 v[80:81], s[52:53], 0, v[80:81]
	v_lshl_add_u64 v[80:81], v[80:81], 0, v[66:67]
	global_load_dwordx2 v[90:91], v[80:81], off
	v_lshl_add_u64 v[84:85], v[84:85], 0, v[66:67]
	v_pk_mul_f32 v[58:59], v[58:59], v[86:87]
	global_load_dwordx2 v[228:229], v[84:85], off
	global_load_dwordx2 v[230:231], v[84:85], off offset:32
	global_load_dwordx2 v[232:233], v[80:81], off offset:32
	global_load_dwordx2 v[234:235], v[84:85], off offset:64
	global_load_dwordx2 v[236:237], v[80:81], off offset:64
	global_load_dwordx2 v[238:239], v[84:85], off offset:96
	global_load_dwordx2 v[240:241], v[80:81], off offset:96
	v_readlane_b32 s36, v214, 34
	v_readlane_b32 s38, v214, 36
	v_readlane_b32 s39, v214, 37
	s_add_u32 s10, s38, s10
	s_addc_u32 s11, s39, s11
	s_lshl_b64 s[6:7], s[6:7], 11
	v_readlane_b32 s37, v214, 35
	v_readlane_b32 s40, v214, 38
	v_readlane_b32 s41, v214, 39
	v_readlane_b32 s42, v214, 40
	v_readlane_b32 s43, v214, 41
	v_readlane_b32 s44, v214, 42
	v_readlane_b32 s45, v214, 43
	v_readlane_b32 s46, v214, 44
	v_readlane_b32 s47, v214, 45
	v_readlane_b32 s48, v214, 46
	v_readlane_b32 s49, v214, 47
	v_readlane_b32 s50, v214, 48
	v_readlane_b32 s51, v214, 49
	s_waitcnt vmcnt(7)
	v_lshlrev_b32_e32 v0, 16, v90
	v_rcp_f32_e32 v94, v0
	v_and_b32_e32 v0, 0xffff0000, v90
	v_rcp_f32_e32 v95, v0
	v_lshlrev_b32_e32 v0, 16, v91
	v_rcp_f32_e32 v90, v0
	v_and_b32_e32 v0, 0xffff0000, v91
	v_rcp_f32_e32 v91, v0
	s_waitcnt vmcnt(6)
	v_lshlrev_b32_e32 v92, 16, v228
	v_and_b32_e32 v93, 0xffff0000, v228
	v_lshlrev_b32_e32 v86, 16, v229
	v_and_b32_e32 v87, 0xffff0000, v229
	v_pk_mul_f32 v[86:87], v[90:91], v[86:87]
	v_pk_mul_f32 v[92:93], v[94:95], v[92:93]
	v_pk_mul_f32 v[52:53], v[52:53], v[86:87]
	v_pk_mul_f32 v[50:51], v[50:51], v[92:93]
	s_waitcnt vmcnt(5)
	v_lshlrev_b32_e32 v92, 16, v230
	s_waitcnt vmcnt(4)
	v_lshlrev_b32_e32 v0, 16, v232
	v_rcp_f32_e32 v94, v0
	v_and_b32_e32 v0, 0xffff0000, v232
	v_rcp_f32_e32 v95, v0
	v_lshlrev_b32_e32 v0, 16, v233
	v_rcp_f32_e32 v90, v0
	v_and_b32_e32 v0, 0xffff0000, v233
	v_rcp_f32_e32 v91, v0
	v_and_b32_e32 v93, 0xffff0000, v230
	v_lshlrev_b32_e32 v86, 16, v231
	v_and_b32_e32 v87, 0xffff0000, v231
	v_pk_mul_f32 v[86:87], v[90:91], v[86:87]
	v_pk_mul_f32 v[92:93], v[94:95], v[92:93]
	v_pk_mul_f32 v[44:45], v[44:45], v[86:87]
	v_pk_mul_f32 v[42:43], v[42:43], v[92:93]
	s_waitcnt vmcnt(3)
	v_lshlrev_b32_e32 v92, 16, v234
	s_waitcnt vmcnt(2)
	v_lshlrev_b32_e32 v0, 16, v236
	v_rcp_f32_e32 v94, v0
	v_and_b32_e32 v0, 0xffff0000, v236
	v_rcp_f32_e32 v95, v0
	v_lshlrev_b32_e32 v0, 16, v237
	v_rcp_f32_e32 v90, v0
	v_and_b32_e32 v0, 0xffff0000, v237
	v_rcp_f32_e32 v91, v0
	v_and_b32_e32 v93, 0xffff0000, v234
	v_lshlrev_b32_e32 v86, 16, v235
	v_and_b32_e32 v87, 0xffff0000, v235
	v_pk_mul_f32 v[86:87], v[90:91], v[86:87]
	v_pk_mul_f32 v[92:93], v[94:95], v[92:93]
	v_pk_mul_f32 v[36:37], v[36:37], v[86:87]
	s_nop 0
	v_pk_mul_f32 v[34:35], v[34:35], v[92:93]
	s_waitcnt vmcnt(1)
	v_lshlrev_b32_e32 v90, 16, v238
	s_waitcnt vmcnt(0)
	v_lshlrev_b32_e32 v0, 16, v240
	v_rcp_f32_e32 v92, v0
	v_and_b32_e32 v0, 0xffff0000, v240
	v_rcp_f32_e32 v93, v0
	v_lshlrev_b32_e32 v0, 16, v241
	v_rcp_f32_e32 v86, v0
	v_and_b32_e32 v0, 0xffff0000, v241
	v_rcp_f32_e32 v87, v0
	v_and_b32_e32 v91, 0xffff0000, v238
	v_lshlrev_b32_e32 v84, 16, v239
	v_and_b32_e32 v85, 0xffff0000, v239
	v_pk_mul_f32 v[84:85], v[86:87], v[84:85]
	v_ashrrev_i32_e32 v94, 6, v96
	v_bfe_u32 v0, v96, 3, 3
	v_pk_mul_f32 v[28:29], v[28:29], v[84:85]
	v_lshl_or_b32 v84, v94, 3, v0
	v_ashrrev_i32_e32 v85, 31, v84
	v_pk_mul_f32 v[90:91], v[92:93], v[90:91]
	v_bitop3_b32 v0, v0, v96, 7 bitop3:0x78
	v_lshlrev_b64 v[86:87], 11, v[84:85]
	v_pk_mul_f32 v[26:27], v[26:27], v[90:91]
	v_lshlrev_b32_e32 v0, 4, v0
	v_lshl_add_u64 v[90:91], s[10:11], 0, v[86:87]
	v_lshl_add_u64 v[92:93], v[90:91], 0, v[0:1]
	v_lshlrev_b32_e32 v90, 10, v94
	v_add_u32_e32 v91, 0x8000, v90
	v_lshl_add_u64 v[84:85], s[12:13], 0, v[86:87]
	v_readfirstlane_b32 s10, v91
	s_mov_b32 m0, s10
	v_readfirstlane_b32 s10, v90
	v_add_u32_e32 v91, 0x9000, v90
	v_lshl_add_u64 v[84:85], v[84:85], 0, v[0:1]
	global_load_lds_dwordx4 v[92:93], off
	s_mov_b32 m0, s10
	s_mov_b64 s[12:13], 0x10000
	v_readfirstlane_b32 s10, v91
	v_add_u32_e32 v91, 0x1000, v90
	global_load_lds_dwordx4 v[84:85], off
	v_lshl_add_u64 v[94:95], v[92:93], 0, s[12:13]
	s_mov_b32 m0, s10
	v_readfirstlane_b32 s10, v91
	v_add_u32_e32 v91, 0xa000, v90
	global_load_lds_dwordx4 v[94:95], off
	v_lshl_add_u64 v[94:95], v[84:85], 0, s[12:13]
	s_mov_b32 m0, s10
	s_mov_b64 s[12:13], 0x20000
	v_readfirstlane_b32 s10, v91
	v_add_u32_e32 v91, 0x2000, v90
	global_load_lds_dwordx4 v[94:95], off
	v_lshl_add_u64 v[94:95], v[92:93], 0, s[12:13]
	s_mov_b32 m0, s10
	v_readfirstlane_b32 s10, v91
	v_add_u32_e32 v91, 0xb000, v90
	global_load_lds_dwordx4 v[94:95], off
	v_lshl_add_u64 v[94:95], v[84:85], 0, s[12:13]
	s_mov_b32 m0, s10
	s_mov_b64 s[12:13], 0x30000
	v_readfirstlane_b32 s10, v91
	v_add_u32_e32 v91, 0x3000, v90
	global_load_lds_dwordx4 v[94:95], off
	v_lshl_add_u64 v[92:93], v[92:93], 0, s[12:13]
	s_mov_b32 m0, s10
	v_readfirstlane_b32 s10, v91
	global_load_lds_dwordx4 v[92:93], off
	v_lshl_add_u64 v[84:85], v[84:85], 0, s[12:13]
	s_mov_b32 m0, s10
	v_lshrrev_b32_e32 v91, 1, v96
	global_load_lds_dwordx4 v[84:85], off
	v_and_b32_e32 v85, 15, v96
	s_mov_b32 s10, 0x1ffffc0
	v_and_or_b32 v85, v91, s10, v85
	v_and_b32_e32 v97, 7, v96
	v_bfe_u32 v84, v96, 4, 2
	v_lshlrev_b32_e32 v92, 7, v85
	v_lshlrev_b32_e32 v85, 7, v96
	v_and_b32_e32 v91, 0x2780, v85
	v_bitop3_b32 v85, v84, v96, 7 bitop3:0x78
	v_bitop3_b32 v84, v84, v97, 4 bitop3:0x36
	s_nop 0
	v_lshlrev_b32_e32 v94, 4, v85
	v_lshlrev_b32_e32 v93, 4, v84
	v_lshl_add_u64 v[84:85], s[6:7], 0, v[86:87]
	v_lshl_add_u64 v[86:87], s[8:9], 0, v[86:87]
	v_or_b32_e32 v84, v84, v0
	v_or_b32_e32 v86, v86, v0
	v_lshl_add_u64 v[84:85], s[4:5], 0, v[84:85]
	v_lshl_add_u64 v[86:87], s[54:55], 0, v[86:87]
	s_mov_b64 s[6:7], 0
	s_mov_b32 s8, 0
	s_waitcnt vmcnt(0) lgkmcnt(0)
	s_barrier
; template <int AMODE>
; __device__ __forceinline__ void gemm_kloop(f32x4 (&acc)[4][4], const u16* __restrict__ A, int lda,
;                                            const u16* __restrict__ Bt, int ldb, int K, char* smem,
;                                            const float* __restrict__ ssq_rows) {
;     ...
;     const int grow = wid * 8 + (lane >> 3);
;     const int gch = ((lane & 7) ^ ((lane >> 3) & 7)) * 8;
;     const u16* Ag = A + (size_t)grow * lda + gch;
;     const u16* Bg = Bt + (size_t)grow * ldb + gch;
	v_lshrrev_b32_e32 v220, 6, v141
	v_bfe_u32 v221, v141, 3, 3
	v_lshl_or_b32 v216, v220, 3, v221
	v_and_b32_e32 v222, 7, v141
	v_xor_b32_e32 v222, v222, v221
	v_lshlrev_b32_e32 v222, 4, v222
	v_lshl_or_b32 v216, v216, 11, v222
	v_add_u32_e32 v217, 0x10000, v216
	v_add_u32_e32 v218, 0x20000, v216
	v_add_u32_e32 v219, 0x30000, v216
	v_readfirstlane_b32 s10, v220
	s_lshl_b32 s10, s10, 14
	v_readfirstlane_b32 s100, v84
	v_readfirstlane_b32 s101, v85
	s_sub_u32 s100, s100, s10
	s_subb_u32 s101, s101, 0
	v_readfirstlane_b32 s98, v86
	v_readfirstlane_b32 s99, v87
	s_sub_u32 s98, s98, s10
	s_subb_u32 s99, s99, 0

; __device__ __forceinline__ int opaque_tid() { int t = threadIdx.x; asm volatile("" : "+v"(t)); return t; }
; template <int AMODE>
; __device__ __forceinline__ void gemm_kloop(f32x4 (&acc)[4][4], const u16* __restrict__ A, int lda,
;                                            const u16* __restrict__ Bt, int ldb, int K, char* smem,
;                                            const float* __restrict__ ssq_rows) {
;     const int tid = opaque_tid(), lane = tid & 63, wid = tid >> 6, wr = wid >> 1, wc = wid & 1;
;     const int r = lane & 15, g4 = lane >> 4;
;     char* As = smem; char* Bs = smem + 32768;
;     const int grow = wid * 8 + (lane >> 3);
;     const int gch = ((lane & 7) ^ ((lane >> 3) & 7)) * 8;
;     const u16* Ag = A + (size_t)grow * lda + gch;
;     const u16* Bg = Bt + (size_t)grow * ldb + gch;
;     const int lrow = tid >> 3, lkc = tid & 7;
;     const u16* Ap = A + (size_t)lrow * lda + lkc * 8;
;     const int lds_w = lrow * 128 + ((lkc ^ (lrow & 7)) << 4);
;     uint4 ra[4];
;     float rs[4];
;     const int nk = K >> 6;
;     ...
;     GLOAD(0, 0);
;     LSTORE(0);
;     asm volatile("s_waitcnt vmcnt(0)" ::: "memory");
;     __syncthreads();
.LBB0_755:
	s_lshl_b32 s0, s11, 7
	s_ashr_i32 s1, s0, 31
	s_lshl_b32 s6, s12, 7
	s_lshl_b64 s[8:9], s[0:1], 11
	v_readlane_b32 s80, v213, 4
	v_readlane_b32 s81, v213, 5
	s_add_u32 s14, s80, s8
	s_addc_u32 s15, s81, s9
	s_ashr_i32 s7, s6, 31
	s_add_u32 s16, s6, s2
	v_mov_b32_e32 v10, v141
	s_addc_u32 s17, s7, 0
	v_readlane_b32 s36, v214, 34
	s_lshl_b64 s[16:17], s[16:17], 11
	v_ashrrev_i32_e32 v8, 6, v10
	v_bfe_u32 v0, v10, 3, 3
	v_readlane_b32 s40, v214, 38
	v_lshl_or_b32 v2, v8, 3, v0
	v_readlane_b32 s41, v214, 39
	s_add_u32 s16, s40, s16
	v_ashrrev_i32_e32 v3, 31, v2
	v_lshlrev_b32_e32 v70, 10, v8
	s_addc_u32 s17, s41, s17
	v_bitop3_b32 v0, v0, v10, 7 bitop3:0x78
	v_lshlrev_b64 v[2:3], 11, v[2:3]
	v_add_u32_e32 v8, 0x8000, v70
	v_lshlrev_b32_e32 v0, 4, v0
	v_lshl_add_u64 v[6:7], s[16:17], 0, v[2:3]
	v_readfirstlane_b32 s1, v8
	v_lshl_add_u64 v[4:5], s[14:15], 0, v[2:3]
	v_lshl_add_u64 v[6:7], v[6:7], 0, v[0:1]
	s_mov_b32 m0, s1
	v_readfirstlane_b32 s1, v70
	v_add_u32_e32 v12, 0x9000, v70
	v_lshl_add_u64 v[4:5], v[4:5], 0, v[0:1]
	global_load_lds_dwordx4 v[6:7], off
	s_mov_b32 m0, s1
	s_mov_b64 s[14:15], 0x10000
	v_readfirstlane_b32 s1, v12
	v_add_u32_e32 v12, 0x1000, v70
	global_load_lds_dwordx4 v[4:5], off
	v_lshl_add_u64 v[8:9], v[6:7], 0, s[14:15]
	s_mov_b32 m0, s1
	v_readfirstlane_b32 s1, v12
	v_add_u32_e32 v12, 0xa000, v70
	global_load_lds_dwordx4 v[8:9], off
	v_lshl_add_u64 v[8:9], v[4:5], 0, s[14:15]
	s_mov_b32 m0, s1
	s_mov_b64 s[14:15], 0x20000
	v_readfirstlane_b32 s1, v12
	v_add_u32_e32 v12, 0x2000, v70
	global_load_lds_dwordx4 v[8:9], off
	v_lshl_add_u64 v[8:9], v[6:7], 0, s[14:15]
	s_mov_b32 m0, s1
	v_readfirstlane_b32 s1, v12
	global_load_lds_dwordx4 v[8:9], off
	v_lshl_add_u64 v[8:9], v[4:5], 0, s[14:15]
	s_mov_b32 m0, s1
	s_mov_b64 s[14:15], 0x30000
	global_load_lds_dwordx4 v[8:9], off
	v_add_u32_e32 v8, 0xb000, v70
	v_lshl_add_u64 v[6:7], v[6:7], 0, s[14:15]
	v_readfirstlane_b32 s1, v8
	s_mov_b32 m0, s1
	v_lshl_add_u64 v[4:5], v[4:5], 0, s[14:15]
	global_load_lds_dwordx4 v[6:7], off
	v_add_u32_e32 v6, 0x3000, v70
	v_and_b32_e32 v11, 7, v10
	v_readfirstlane_b32 s1, v6
	s_mov_b32 m0, s1
	v_lshrrev_b32_e32 v6, 1, v10
	global_load_lds_dwordx4 v[4:5], off
	v_and_b32_e32 v5, 15, v10
	s_mov_b32 s1, 0x1ffffc0
	v_and_or_b32 v5, v6, s1, v5
	v_bfe_u32 v4, v10, 4, 2
	v_lshlrev_b32_e32 v72, 7, v5
	v_lshlrev_b32_e32 v5, 7, v10
	v_and_b32_e32 v71, 0x2780, v5
	v_bitop3_b32 v5, v4, v10, 7 bitop3:0x78
	v_bitop3_b32 v4, v4, v11, 4 bitop3:0x36
	s_lshl_b64 s[14:15], s[6:7], 11
	v_lshlrev_b32_e32 v77, 4, v5
	v_lshlrev_b32_e32 v73, 4, v4
	v_lshl_add_u64 v[4:5], s[14:15], 0, v[2:3]
	v_lshl_add_u64 v[2:3], s[8:9], 0, v[2:3]
	s_nop 0
	v_or_b32_e32 v2, v2, v0
	v_or_b32_e32 v4, v4, v0
	v_lshl_add_u64 v[68:69], s[80:81], 0, v[2:3]
	v_mov_b32_e32 v2, 0
	v_lshl_add_u64 v[66:67], s[4:5], 0, v[4:5]
	s_mov_b64 s[8:9], 0
	s_mov_b32 s1, 0
	v_mov_b32_e32 v3, v2
	v_mov_b32_e32 v4, v2
	v_mov_b32_e32 v5, v2
	v_mov_b32_e32 v6, v2
	v_mov_b32_e32 v7, v2
	v_mov_b32_e32 v8, v2
	v_mov_b32_e32 v9, v2
	v_mov_b32_e32 v10, v2
	v_mov_b32_e32 v11, v2
	v_mov_b32_e32 v12, v2
	v_mov_b32_e32 v13, v2
	v_mov_b32_e32 v14, v2
	v_mov_b32_e32 v15, v2
	v_mov_b32_e32 v16, v2
	v_mov_b32_e32 v17, v2
	v_mov_b32_e32 v18, v2
	v_mov_b32_e32 v19, v2
	v_mov_b32_e32 v20, v2
	v_mov_b32_e32 v21, v2
	v_mov_b32_e32 v22, v2
	v_mov_b32_e32 v23, v2
	v_mov_b32_e32 v24, v2
	v_mov_b32_e32 v25, v2
	v_mov_b32_e32 v26, v2
	v_mov_b32_e32 v27, v2
	v_mov_b32_e32 v28, v2
	v_mov_b32_e32 v29, v2
	v_mov_b32_e32 v30, v2
	v_mov_b32_e32 v31, v2
	v_mov_b32_e32 v32, v2
	v_mov_b32_e32 v33, v2
	v_mov_b32_e32 v34, v2
	v_mov_b32_e32 v35, v2
	v_mov_b32_e32 v36, v2
	v_mov_b32_e32 v37, v2
	v_mov_b32_e32 v38, v2
	v_mov_b32_e32 v39, v2
	v_mov_b32_e32 v40, v2
	v_mov_b32_e32 v41, v2
	v_mov_b32_e32 v42, v2
	v_mov_b32_e32 v43, v2
	v_mov_b32_e32 v44, v2
	v_mov_b32_e32 v45, v2
	v_mov_b32_e32 v46, v2
	v_mov_b32_e32 v47, v2
	v_mov_b32_e32 v48, v2
	v_mov_b32_e32 v49, v2
	v_mov_b32_e32 v50, v2
	v_mov_b32_e32 v51, v2
	v_mov_b32_e32 v52, v2
	v_mov_b32_e32 v53, v2
	v_mov_b32_e32 v54, v2
	v_mov_b32_e32 v55, v2
	v_mov_b32_e32 v56, v2
	v_mov_b32_e32 v57, v2
	v_mov_b32_e32 v58, v2
	v_mov_b32_e32 v59, v2
	v_mov_b32_e32 v60, v2
	v_mov_b32_e32 v61, v2
	v_mov_b32_e32 v62, v2
	v_mov_b32_e32 v63, v2
	v_mov_b32_e32 v64, v2
	v_mov_b32_e32 v65, v2
	v_readlane_b32 s82, v213, 6
	v_readlane_b32 s83, v213, 7
	v_readlane_b32 s84, v213, 8
	v_readlane_b32 s85, v213, 9
	v_readlane_b32 s86, v213, 10
	v_readlane_b32 s87, v213, 11
	v_readlane_b32 s88, v213, 12
	v_readlane_b32 s89, v213, 13
	v_readlane_b32 s90, v213, 14
	v_readlane_b32 s91, v213, 15
	v_readlane_b32 s92, v213, 16
	v_readlane_b32 s93, v213, 17
	v_readlane_b32 s94, v213, 18
	v_readlane_b32 s95, v213, 19
	v_readlane_b32 s37, v214, 35
	v_readlane_b32 s38, v214, 36
	v_readlane_b32 s39, v214, 37
	v_readlane_b32 s42, v214, 40
	v_readlane_b32 s43, v214, 41
	v_readlane_b32 s44, v214, 42
	v_readlane_b32 s45, v214, 43
	v_readlane_b32 s46, v214, 44
	v_readlane_b32 s47, v214, 45
	v_readlane_b32 s48, v214, 46
	v_readlane_b32 s49, v214, 47
	v_readlane_b32 s50, v214, 48
	v_readlane_b32 s51, v214, 49
	s_waitcnt vmcnt(0) lgkmcnt(0)
	s_barrier
	v_lshrrev_b32_e32 v220, 6, v141
	v_bfe_u32 v221, v141, 3, 3
	v_lshl_or_b32 v216, v220, 3, v221
	v_and_b32_e32 v222, 7, v141
	v_xor_b32_e32 v222, v222, v221
	v_lshlrev_b32_e32 v222, 4, v222
	v_lshl_or_b32 v216, v216, 11, v222
	v_add_u32_e32 v217, 0x10000, v216
	v_add_u32_e32 v218, 0x20000, v216
	v_add_u32_e32 v219, 0x30000, v216
	v_readfirstlane_b32 s13, v220
	s_lshl_b32 s13, s13, 14
	v_readfirstlane_b32 s100, v66
	v_readfirstlane_b32 s101, v67
	s_sub_u32 s100, s100, s13
	s_subb_u32 s101, s101, 0
	v_readfirstlane_b32 s98, v68
	v_readfirstlane_b32 s99, v69
	s_sub_u32 s98, s98, s13
	s_subb_u32 s99, s99, 0
